# MLA up-projection: ukv GEMM walks its tiles in reverse workgroup order to balance the uq+ukv phase (3rd ukv tile goes to workgroups with one uq tile)
# speedup vs baseline: 1.0111x; 1.0018x over previous
; #define LAS __attribute__((address_space(3)))
; #define PG8_STAGE(bufoff, gbase) do { _Pragma("unroll") for (int _i = 0; _i < 2; ++_i) \
;         __builtin_amdgcn_global_load_lds((const unsigned*)((const char*)(gbase) + voffA[_i]), (LAS unsigned*)(lds + (bufoff) + ldsw + _i * 8192), 16, 0, 0); } while (0)
; #define PG8_WAIT_V(n) asm volatile("s_waitcnt vmcnt(" #n ")" ::: "memory")
; #define PG8_BAR __builtin_amdgcn_s_barrier()
; template <class Epi>
; DI void gemm_phase(const int TID, const int BID, LAS unsigned char* lds, const Gemm g, const Epi& E) {
;     const int tid = TID, wid = __builtin_amdgcn_readfirstlane(tid >> 6), lane = tid & 63, wr = wid >> 2, wc = wid & 3, fr = lane & 15, fq = lane >> 4;
;     int K = g.K; asm volatile("" : "+s"(K));
;     StaticOrder S; S.init(g.M, g.N, K, g.nsplit, (int)gridDim.x, BID);
;     unsigned voffA[2];
; #pragma unroll
;     for (int i = 0; i < 2; ++i) { int R, C; stage_rc(tid * 16 + i * 8192, R, C); voffA[i] = (unsigned)(R * K + C) * 2u; }
;     const size_t kstep = (size_t)(BK * 2);
;     const size_t hstep = (size_t)HALF * K * 2;
;     const size_t tstep = 2 * hstep;
;     const unsigned ldsw = (unsigned)wid * 1024u;
;     const int aoff = lds_byte(wr * 64 + fr, fq * 8), boff = lds_byte(wc * 32 + fr, fq * 8);
;     ...
;     Unit cur, nxt; int ui = 0;
;     if (!S.next(0, cur)) return;
;     f32x4 acc[2][2][4][2];
; #pragma unroll
;     for (int a = 0; a < 2; ++a)
; #pragma unroll
;         for (int b = 0; b < 2; ++b)
; #pragma unroll
;             for (int m = 0; m < 4; ++m)
; #pragma unroll
;                 for (int n = 0; n < 2; ++n) acc[a][b][m][n] = (f32x4){0.f, 0.f, 0.f, 0.f};
;     bf16x8 At[4][2], B0[2][2], B1[2][2];
;     const char* cA = (const char*)g.A + (size_t)cur.pm * tstep + (size_t)cur.k0 * 2; const char* cB = (const char*)g.Bt + (size_t)cur.pn * tstep + (size_t)cur.k0 * 2;
;     PG8_STAGE(PG8_SB(0, 0), cB); PG8_STAGE(PG8_SA(0, 0), cA); PG8_STAGE(PG8_SB(0, 1), cB + hstep); PG8_STAGE(PG8_SA(0, 1), cA + hstep);
;     if (wr == 1) PG8_BAR;
;     PG8_WAIT_V(4); PG8_BAR;
;     PG8_STAGE(PG8_SB(1, 0), cB + kstep); PG8_STAGE(PG8_SA(1, 0), cA + kstep); PG8_STAGE(PG8_SB(1, 1), cB + hstep + kstep);
;     PG8_WAIT_V(6); PG8_BAR;
.LBB0_478:
	s_sub_i32 s83, s31, s83
	s_add_i32 s83, s83, -1
	v_readfirstlane_b32 s41, v174
	s_movk_i32 s0, 0x100
	s_cmpk_gt_i32 s83, 0x23f
	s_cbranch_scc1 .LBB0_500
	v_readlane_b32 s2, v255, 22
	v_readlane_b32 s3, v255, 23
	s_lshl_b64 s[2:3], s[2:3], 20
	v_readlane_b32 s1, v254, 7
	s_add_u32 s42, s1, s2
	v_readlane_b32 s1, v254, 8
	s_addc_u32 s17, s1, s3
	s_lshr_b32 s2, s40, 29
	s_add_i32 s2, s83, s2
	s_ashr_i32 s10, s41, 6
	s_ashr_i32 s1, s0, 31
	s_ashr_i32 s4, s2, 3
	s_and_b32 s2, s2, -8
	s_ashr_i32 s3, s41, 8
	s_lshl_b64 s[6:7], s[0:1], 8
	s_lshl_b64 s[8:9], s[0:1], 9
	s_lshl_b32 s11, s10, 10
	s_sub_i32 s2, s83, s2
	s_cmp_lt_i32 s2, 0
	s_movk_i32 s5, 0x49
	s_cselect_b32 s5, s5, 0x48
	s_mul_i32 s2, s5, s2
	s_add_i32 s2, s2, s4
	s_ashr_i32 s4, s2, 31
	s_lshr_b32 s4, s4, 26
	s_add_i32 s4, s2, s4
	s_ashr_i32 s5, s4, 6
	s_and_b32 s4, s4, 0xffc0
	s_sub_i32 s4, s2, s4
	s_bfe_i32 s2, s4, 0x80000
	s_bfe_u32 s2, s2, 0x3000c
	s_add_i32 s12, s4, s2
	s_bfe_i32 s2, s12, 0x80000
	s_and_b32 s12, s12, 0xf8
	s_sub_i32 s4, s4, s12
	s_lshl_b32 s5, s5, 3
	s_sext_i32_i8 s4, s4
	s_add_i32 s84, s5, s4
	s_ashr_i32 s4, s84, 31
	s_mul_i32 s4, s8, s4
	s_mul_hi_u32 s5, s8, s84
	s_sext_i32_i16 s15, s2
	s_add_i32 s12, s5, s4
	s_lshr_b64 s[4:5], s[0:1], 23
	s_lshr_b32 s2, s15, 3
	s_mul_i32 s5, s4, s84
	s_add_i32 s5, s12, s5
	s_bfe_i64 s[12:13], s[2:3], 0x100000
	s_ashr_i32 s12, s15, 3
	s_mul_hi_u32 s15, s8, s12
	s_mul_i32 s13, s8, s13
	s_add_i32 s13, s15, s13
	s_mul_i32 s4, s4, s12
	s_add_i32 s13, s13, s4
	s_mul_i32 s4, s8, s12
	s_add_u32 s60, s42, s4
	s_addc_u32 s61, s17, s13
	s_add_i32 s18, s23, 0x10000
	s_add_i32 s19, s18, s11
	s_mul_i32 s16, s8, s84
	s_add_i32 s20, s19, 0x2000
	v_readlane_b32 s12, v254, 44
	v_readlane_b32 s13, v254, 45
	s_add_u32 s4, s12, s16
	v_mul_lo_u32 v12, s0, v186
	s_addc_u32 s5, s13, s5
	s_add_i32 s21, s23, s11
	v_mul_lo_u32 v0, s0, v188
	v_add_lshl_u32 v160, v12, v187, 1
	s_mov_b32 m0, s19
	s_add_i32 s22, s21, 0x2000
	v_add_lshl_u32 v158, v0, v189, 1
	global_load_lds_dwordx4 v160, s[60:61]
	s_mov_b32 m0, s20
	s_add_u32 s12, s60, s6
	global_load_lds_dwordx4 v158, s[60:61]
	s_mov_b32 m0, s21
	s_addc_u32 s13, s61, s7
	s_add_i32 s23, s23, 0x14000
	global_load_lds_dwordx4 v160, s[4:5]
	s_mov_b32 m0, s22
	s_add_i32 s24, s23, s11
	global_load_lds_dwordx4 v158, s[4:5]
	s_mov_b32 m0, s24
	s_add_i32 s25, s24, 0x2000
	v_mov_b32_e32 v161, v169
	v_mov_b32_e32 v159, v169
	global_load_lds_dwordx4 v160, s[12:13]
	s_mov_b32 m0, s25
	v_lshl_add_u64 v[8:9], s[12:13], 0, v[160:161]
	v_lshl_add_u64 v[10:11], s[12:13], 0, v[158:159]
	global_load_lds_dwordx4 v158, s[12:13]
	s_add_u32 s12, s4, s6
	s_addc_u32 s13, s5, s7
	s_add_i32 s26, s21, 0x4000
	s_mov_b32 m0, s26
	s_add_i32 s27, s21, 0x6000
	global_load_lds_dwordx4 v160, s[12:13]
	s_mov_b32 m0, s27
	s_mov_b32 s38, 0x358637bd
	global_load_lds_dwordx4 v158, s[12:13]
	v_lshl_add_u64 v[0:1], s[60:61], 0, v[160:161]
	v_lshl_add_u64 v[2:3], s[60:61], 0, v[158:159]
	v_lshl_add_u64 v[4:5], s[4:5], 0, v[160:161]
	v_lshl_add_u64 v[6:7], s[4:5], 0, v[158:159]
	s_cmp_lg_u32 s3, 1
	s_cbranch_scc1 .LBB0_481
	s_barrier
